# sync micro-edits combined: barrier kernarg loads before the workgroup barrier, no invalidate in the mod-item release, no wait after the entry census atomic (covered by the release's vmcnt(0))
# speedup vs baseline: 1.0011x; 1.0011x over previous
; DI int tid_() { int t = threadIdx.x; asm volatile("" : "+v"(t)); return t; }
; DI void phase0a(const Params& p, char* smem) {
;   const int t = tid_();
;   const int nMod = 384, nPos = 288, nMisc = 3;
;   for (int it = blockIdx.x; it < nMod; it += gridDim.x) {
;     mod_item(p, it, smem);
;     __syncthreads();
;     if (t == 0) { __threadfence(); atomicAdd(p.modctr, 1u); }
; __global__ void __launch_bounds__(NTH, 2) mega_kernel(Params p) {
;   cg::grid_group grid = cg::this_grid();
;   __shared__ __attribute__((aligned(16))) char smem[SMEM_BYTES];
;     ...
;   phase0a(p, smem);
_Z11mega_kernel6Params:
	s_load_dword s3, s[0:1], 0x490
	s_add_u32 s4, s0, 0x490
	s_addc_u32 s5, s1, 0
	v_and_b32_e32 v220, 0x3ff, v0
	v_writelane_b32 v252, s4, 0
	v_mov_b32_e32 v2, v220
	v_cmp_eq_u32_e32 vcc, 0, v220
	s_and_b64 exec, exec, vcc
	s_cbranch_execz .Lcen_skip
	s_load_dwordx2 s[98:99], s[0:1], 0x158
	s_getreg_b32 s100, hwreg(HW_REG_XCC_ID, 0, 4)
	v_mov_b32_e32 v1, 1
	s_lshl_b32 s100, s100, 2
	v_mov_b32_e32 v3, s100
	s_waitcnt lgkmcnt(0)
	global_atomic_add v3, v1, s[98:99] offset:192
.Lcen_skip:
	s_mov_b64 exec, -1
	s_cmpk_gt_i32 s2, 0x17f
	v_writelane_b32 v252, s5, 1
	s_cbranch_scc1 .LBB0_17
	s_load_dwordx2 s[14:15], s[0:1], 0x8
	s_load_dwordx4 s[8:11], s[0:1], 0x18
	s_load_dwordx2 s[16:17], s[0:1], 0x28
	s_load_dwordx2 s[18:19], s[0:1], 0xb8
	s_load_dwordx2 s[20:21], s[0:1], 0x158
	s_mov_b32 s13, 0
	v_cmp_eq_u32_e64 s[6:7], 0, v2
	s_movk_i32 s26, 0x6000
	s_waitcnt lgkmcnt(0)
	v_mov_b64_e32 v[4:5], s[10:11]
	v_mov_b32_e32 v7, 0
	s_movk_i32 s27, 0x1080
	s_movk_i32 s28, 0xe7f
	s_movk_i32 s29, 0x840
	s_movk_i32 s30, 0x210
	s_movk_i32 s31, 0x1800
	s_mov_b32 s33, s2
	s_branch .LBB0_3
